# v4 plus w_down weight conversion moved out of P0 into the idle half of the up_proj phase (workgroups 128..255, hand-written routine)
# baseline (speedup 1.0000x reference)
.LBB0_9:
	s_mul_hi_i32 s0, s49, 0x14d843bf
	s_lshr_b32 s1, s0, 31
	s_ashr_i32 s0, s0, 10
	s_add_i32 s12, s0, s1
	s_mul_i32 s0, s12, 0xffffcee0
	s_add_i32 s20, s49, s0
	s_cmpk_gt_i32 s20, 0xc1f
	s_mov_b64 s[0:1], -1
	s_cbranch_scc0 .LBB0_75
	s_cmpk_gt_u32 s20, 0x101f
	s_cbranch_scc0 .LBB0_40
	s_cmpk_gt_u32 s20, 0x261f
	s_cbranch_scc0 .LBB0_13
	s_cmpk_eq_u32 s90, 0x100
	s_cbranch_scc1 .LBB0_8
	v_readlane_b32 s52, v253, 41
	s_mul_i32 s1, s12, 0x2c00000
	v_readlane_b32 s64, v253, 53
	s_mul_hi_i32 s0, s12, 0x2c00000
	v_readlane_b32 s65, v253, 54
	s_add_u32 s1, s64, s1
	s_addc_u32 s13, s65, s0
	s_mul_i32 s14, s12, 0x1600000
	s_mul_hi_i32 s0, s12, 0x1600000
	s_add_u32 s16, s3, s14
	s_addc_u32 s17, s7, s0
	s_mul_i32 s0, s12, 0xffff9dc0
	s_add_i32 s0, s30, s0
	s_addk_i32 s0, 0xcc00
	s_and_b32 s18, s0, 0x1fc0
	s_add_i32 s0, s28, 0xfff98000
	s_and_b32 s0, s0, 0x7c0
	s_lshl_b32 s14, s0, 2
	s_add_u32 s14, s1, s14
	v_or_b32_e32 v4, s18, v67
	s_addc_u32 s15, s13, 0
	v_mov_b32_e32 v73, v69
	v_lshl_add_u64 v[2:3], s[14:15], 0, v[72:73]
	v_lshlrev_b32_e32 v68, 13, v4
	v_lshl_add_u64 v[62:63], v[2:3], 0, v[68:69]
	v_add_co_u32_e32 v6, vcc, s33, v62
	s_mov_b32 s1, 0x70000
	s_nop 0
	v_addc_co_u32_e32 v7, vcc, 0, v63, vcc
	v_add_co_u32_e32 v10, vcc, s34, v62
	global_load_dwordx4 v[2:5], v[62:63], off nt
	s_nop 0
	global_load_dwordx4 v[6:9], v[6:7], off nt
	v_addc_co_u32_e32 v11, vcc, 0, v63, vcc
	v_add_co_u32_e32 v14, vcc, s35, v62
	v_lshlrev_b32_e32 v68, 1, v70
	s_nop 0
	v_addc_co_u32_e32 v15, vcc, 0, v63, vcc
	v_add_co_u32_e32 v18, vcc, s36, v62
	global_load_dwordx4 v[10:13], v[10:11], off nt
	s_nop 0
	global_load_dwordx4 v[14:17], v[14:15], off nt
	v_addc_co_u32_e32 v19, vcc, 0, v63, vcc
	v_add_co_u32_e32 v22, vcc, s37, v62
	v_readlane_b32 s53, v253, 42
	s_nop 0
	v_addc_co_u32_e32 v23, vcc, 0, v63, vcc
	v_add_co_u32_e32 v26, vcc, s38, v62
	global_load_dwordx4 v[18:21], v[18:19], off nt
	s_nop 0
	global_load_dwordx4 v[22:25], v[22:23], off nt
	v_addc_co_u32_e32 v27, vcc, 0, v63, vcc
	v_add_co_u32_e32 v30, vcc, s39, v62
	v_readlane_b32 s54, v253, 43
	s_nop 0
	v_addc_co_u32_e32 v31, vcc, 0, v63, vcc
	v_add_co_u32_e32 v34, vcc, s40, v62
	global_load_dwordx4 v[26:29], v[26:27], off nt
	s_nop 0
	global_load_dwordx4 v[30:33], v[30:31], off nt
	v_addc_co_u32_e32 v35, vcc, 0, v63, vcc
	v_add_co_u32_e32 v38, vcc, s41, v62
	v_readlane_b32 s55, v253, 44
	s_nop 0
	v_addc_co_u32_e32 v39, vcc, 0, v63, vcc
	v_add_co_u32_e32 v42, vcc, s42, v62
	global_load_dwordx4 v[34:37], v[34:35], off nt
	s_nop 0
	global_load_dwordx4 v[38:41], v[38:39], off nt
	v_addc_co_u32_e32 v43, vcc, 0, v63, vcc
	v_add_co_u32_e32 v46, vcc, s43, v62
	v_readlane_b32 s56, v253, 45
	s_nop 0
	v_addc_co_u32_e32 v47, vcc, 0, v63, vcc
	v_add_co_u32_e32 v50, vcc, s44, v62
	global_load_dwordx4 v[42:45], v[42:43], off nt
	s_nop 0
	global_load_dwordx4 v[46:49], v[46:47], off nt
	v_addc_co_u32_e32 v51, vcc, 0, v63, vcc
	v_add_co_u32_e32 v54, vcc, s45, v62
	v_readlane_b32 s57, v253, 46
	s_nop 0
	v_addc_co_u32_e32 v55, vcc, 0, v63, vcc
	v_add_co_u32_e32 v58, vcc, s1, v62
	s_mov_b32 s1, 0x78000
	s_nop 0
	v_addc_co_u32_e32 v59, vcc, 0, v63, vcc
	v_add_co_u32_e32 v62, vcc, s1, v62
	global_load_dwordx4 v[50:53], v[50:51], off nt
	s_nop 0
	global_load_dwordx4 v[54:57], v[54:55], off nt
	v_addc_co_u32_e32 v63, vcc, 0, v63, vcc
	global_load_dwordx4 v[58:61], v[58:59], off nt
	s_lshl_b32 s1, s18, 1
	global_load_dwordx4 v[62:65], v[62:63], off nt
	s_add_u32 s14, s16, s1
	s_addc_u32 s15, s17, 0
	v_readlane_b32 s58, v253, 47
	v_readlane_b32 s59, v253, 48
	v_readlane_b32 s60, v253, 49
	v_readlane_b32 s61, v253, 50
	v_readlane_b32 s62, v253, 51
	v_readlane_b32 s63, v253, 52
	v_readlane_b32 s66, v253, 55
	v_readlane_b32 s67, v253, 56
	s_waitcnt vmcnt(15)
	ds_write2_b32 v97, v2, v3 offset1:1
	ds_write2_b32 v97, v4, v5 offset0:2 offset1:3
	s_waitcnt vmcnt(14)
	ds_write2_b32 v98, v6, v7 offset1:1
	ds_write2_b32 v99, v8, v9 offset1:1
	s_waitcnt vmcnt(13)
	ds_write2_b32 v100, v10, v11 offset1:1
	ds_write2_b32 v101, v12, v13 offset1:1
	s_waitcnt vmcnt(12)
	ds_write2_b32 v102, v14, v15 offset1:1
	ds_write2_b32 v103, v16, v17 offset1:1
	s_waitcnt vmcnt(11)
	ds_write2_b32 v104, v18, v19 offset1:1
	ds_write2_b32 v105, v20, v21 offset1:1
	s_waitcnt vmcnt(10)
	ds_write2_b32 v106, v22, v23 offset1:1
	ds_write2_b32 v107, v24, v25 offset1:1
	s_waitcnt vmcnt(9)
	ds_write2_b32 v108, v26, v27 offset1:1
	ds_write2_b32 v109, v28, v29 offset1:1
	s_waitcnt vmcnt(8)
	ds_write2_b32 v110, v30, v31 offset1:1
	ds_write2_b32 v111, v32, v33 offset1:1
	s_waitcnt vmcnt(7)
	ds_write2_b32 v112, v34, v35 offset1:1
	ds_write2_b32 v113, v36, v37 offset1:1
	s_waitcnt vmcnt(6)
	ds_write2_b32 v114, v38, v39 offset1:1
	ds_write2_b32 v115, v40, v41 offset1:1
	s_waitcnt vmcnt(5)
	ds_write2_b32 v116, v42, v43 offset1:1
	ds_write2_b32 v117, v44, v45 offset1:1
	s_waitcnt vmcnt(4)
	ds_write2_b32 v118, v46, v47 offset1:1
	ds_write2_b32 v119, v48, v49 offset1:1
	s_waitcnt vmcnt(3)
	ds_write2_b32 v120, v50, v51 offset1:1
	ds_write2_b32 v121, v52, v53 offset1:1
	s_waitcnt vmcnt(2)
	ds_write2_b32 v122, v54, v55 offset1:1
	ds_write2_b32 v123, v56, v57 offset1:1
	s_waitcnt vmcnt(1)
	ds_write2_b32 v124, v58, v59 offset1:1
	ds_write2_b32 v125, v60, v61 offset1:1
	s_waitcnt vmcnt(0)
	ds_write2_b32 v126, v62, v63 offset1:1
	v_add_u32_e32 v2, 0x3cf8, v97
	v_add_u32_e32 v26, 0x400, v78
	v_lshl_add_u64 v[22:23], s[14:15], 0, v[68:69]
	ds_write2_b32 v2, v64, v65 offset1:1
	s_waitcnt lgkmcnt(0)
	ds_read2_b32 v[6:7], v78 offset0:65 offset1:73
	ds_read2_b32 v[8:9], v78 offset1:8
	ds_read2_b32 v[10:11], v78 offset0:130 offset1:138
	ds_read2_b32 v[12:13], v78 offset0:195 offset1:203
	ds_read2_b32 v[14:15], v26 offset0:4 offset1:12
	ds_read2_b32 v[16:17], v26 offset0:69 offset1:77
	ds_read2_b32 v[18:19], v26 offset0:134 offset1:142
	ds_read2_b32 v[20:21], v26 offset0:199 offset1:207
	s_waitcnt lgkmcnt(6)
	v_cvt_pk_bf16_f32 v2, v8, v6
	v_or_b32_e32 v6, s0, v77
	v_mul_u32_u24_e32 v68, 0x2c00, v6
	v_lshl_add_u64 v[24:25], v[22:23], 0, v[68:69]
	s_waitcnt lgkmcnt(4)
	v_cvt_pk_bf16_f32 v3, v10, v12
	s_waitcnt lgkmcnt(2)
	v_cvt_pk_bf16_f32 v4, v14, v16
	s_waitcnt lgkmcnt(0)
	v_cvt_pk_bf16_f32 v5, v18, v20
	global_store_dwordx4 v[24:25], v[2:5], off nt
	v_or_b32_e32 v6, s0, v79
	v_mul_u32_u24_e32 v68, 0x2c00, v6
	v_cvt_pk_bf16_f32 v2, v9, v7
	v_cvt_pk_bf16_f32 v3, v11, v13
	v_cvt_pk_bf16_f32 v4, v15, v17
	v_cvt_pk_bf16_f32 v5, v19, v21
	ds_read2_b32 v[8:9], v78 offset0:16 offset1:24
	ds_read2_b32 v[10:11], v78 offset0:81 offset1:89
	ds_read2_b32 v[12:13], v78 offset0:146 offset1:154
	ds_read2_b32 v[14:15], v78 offset0:211 offset1:219
	ds_read2_b32 v[16:17], v26 offset0:20 offset1:28
	ds_read2_b32 v[18:19], v26 offset0:85 offset1:93
	ds_read2_b32 v[20:21], v26 offset0:150 offset1:158
	ds_read2_b32 v[24:25], v26 offset0:215 offset1:223
	v_lshl_add_u64 v[6:7], v[22:23], 0, v[68:69]
	global_store_dwordx4 v[6:7], v[2:5], off nt
	v_or_b32_e32 v6, s0, v80
	v_mul_u32_u24_e32 v68, 0x2c00, v6
	v_lshl_add_u64 v[6:7], v[22:23], 0, v[68:69]
	s_waitcnt lgkmcnt(6)
	v_cvt_pk_bf16_f32 v2, v8, v10
	s_waitcnt lgkmcnt(4)
	v_cvt_pk_bf16_f32 v3, v12, v14
	s_waitcnt lgkmcnt(2)
	v_cvt_pk_bf16_f32 v4, v16, v18
	s_waitcnt lgkmcnt(0)
	v_cvt_pk_bf16_f32 v5, v20, v24
	global_store_dwordx4 v[6:7], v[2:5], off nt
	v_or_b32_e32 v6, s0, v81
	v_mul_u32_u24_e32 v68, 0x2c00, v6
	v_cvt_pk_bf16_f32 v2, v9, v11
	v_cvt_pk_bf16_f32 v3, v13, v15
	v_cvt_pk_bf16_f32 v4, v17, v19
	v_cvt_pk_bf16_f32 v5, v21, v25
	ds_read2_b32 v[8:9], v78 offset0:32 offset1:40
	ds_read2_b32 v[10:11], v78 offset0:97 offset1:105
	ds_read2_b32 v[12:13], v78 offset0:162 offset1:170
	ds_read2_b32 v[14:15], v78 offset0:227 offset1:235
	ds_read2_b32 v[16:17], v26 offset0:36 offset1:44
	ds_read2_b32 v[18:19], v26 offset0:101 offset1:109
	ds_read2_b32 v[20:21], v26 offset0:166 offset1:174
	ds_read2_b32 v[24:25], v26 offset0:231 offset1:239
	v_lshl_add_u64 v[6:7], v[22:23], 0, v[68:69]
	global_store_dwordx4 v[6:7], v[2:5], off nt
	v_or_b32_e32 v6, s0, v82
	v_mul_u32_u24_e32 v68, 0x2c00, v6
	v_lshl_add_u64 v[6:7], v[22:23], 0, v[68:69]
	s_waitcnt lgkmcnt(6)
	v_cvt_pk_bf16_f32 v2, v8, v10
	s_waitcnt lgkmcnt(4)
	v_cvt_pk_bf16_f32 v3, v12, v14
	s_waitcnt lgkmcnt(2)
	v_cvt_pk_bf16_f32 v4, v16, v18
	s_waitcnt lgkmcnt(0)
	v_cvt_pk_bf16_f32 v5, v20, v24
	global_store_dwordx4 v[6:7], v[2:5], off nt
	v_or_b32_e32 v6, s0, v83
	v_mul_u32_u24_e32 v68, 0x2c00, v6
	v_cvt_pk_bf16_f32 v2, v9, v11
	v_cvt_pk_bf16_f32 v3, v13, v15
	v_cvt_pk_bf16_f32 v4, v17, v19
	v_cvt_pk_bf16_f32 v5, v21, v25
	ds_read2_b32 v[8:9], v78 offset0:48 offset1:56
	ds_read2_b32 v[10:11], v78 offset0:113 offset1:121
	ds_read2_b32 v[12:13], v78 offset0:178 offset1:186
	ds_read2_b32 v[14:15], v78 offset0:243 offset1:251
	ds_read2_b32 v[16:17], v26 offset0:52 offset1:60
	ds_read2_b32 v[18:19], v26 offset0:117 offset1:125
	ds_read2_b32 v[20:21], v26 offset0:182 offset1:190
	ds_read2_b32 v[24:25], v26 offset0:247 offset1:255
	v_lshl_add_u64 v[6:7], v[22:23], 0, v[68:69]
	global_store_dwordx4 v[6:7], v[2:5], off nt
	v_or_b32_e32 v6, s0, v84
	v_mul_u32_u24_e32 v68, 0x2c00, v6
	v_lshl_add_u64 v[6:7], v[22:23], 0, v[68:69]
	s_waitcnt lgkmcnt(6)
	v_cvt_pk_bf16_f32 v2, v8, v10
	s_waitcnt lgkmcnt(4)
	v_cvt_pk_bf16_f32 v3, v12, v14
	s_waitcnt lgkmcnt(2)
	v_cvt_pk_bf16_f32 v4, v16, v18
	s_waitcnt lgkmcnt(0)
	v_cvt_pk_bf16_f32 v5, v20, v24
	global_store_dwordx4 v[6:7], v[2:5], off nt
	v_or_b32_e32 v6, s0, v85
	v_mul_u32_u24_e32 v68, 0x2c00, v6
	v_lshl_add_u64 v[6:7], v[22:23], 0, v[68:69]
	v_cvt_pk_bf16_f32 v2, v9, v11
	v_cvt_pk_bf16_f32 v3, v13, v15
	v_cvt_pk_bf16_f32 v4, v17, v19
	v_cvt_pk_bf16_f32 v5, v21, v25
	global_store_dwordx4 v[6:7], v[2:5], off nt
	s_waitcnt lgkmcnt(0)
	s_mov_b64 s[0:1], 0

.LBB0_166:
	v_ashrrev_i32_e32 v9, 31, v8
	v_lshrrev_b32_e32 v9, 20, v9
	v_add_u32_e32 v9, v8, v9
	v_ashrrev_i32_e32 v9, 12, v9
	v_mul_i32_i24_e32 v13, 0x1000, v9
	v_sub_u32_e32 v14, v8, v13
	v_mad_i64_i32 v[10:11], s[8:9], v9, s3, v[6:7]
	v_add_u32_e32 v8, s33, v8
	v_ashrrev_i32_e32 v15, 31, v14
	v_cmp_lt_i32_e32 vcc, s7, v8
	v_lshl_add_u64 v[10:11], v[14:15], 4, v[10:11]
	s_or_b64 s[4:5], vcc, s[4:5]
	v_add_co_u32_e32 v10, vcc, 0x1910000, v10
	s_nop 1
	v_addc_co_u32_e32 v11, vcc, 0, v11, vcc
	global_store_dwordx4 v[10:11], v[2:5], off nt
	s_andn2_b64 exec, exec, s[4:5]
	s_cbranch_execnz .LBB0_166

.LBB0_1417:
.Lwd_entry:
	s_cmpk_lg_u32 s90, 0x100
	s_cbranch_scc1 .Lwd_done
	v_readlane_b32 s12, v254, 62
	s_cmpk_lt_u32 s12, 0x80
	s_cbranch_scc1 .Lwd_done
	v_readfirstlane_b32 s4, v0
	s_lshr_b32 s11, s4, 6
	s_sub_i32 s5, s12, 0x80
	s_lshl_b32 s5, s5, 3
	s_add_i32 s4, s11, s5
	v_readlane_b32 s10, v255, 0
	v_readlane_b32 s0, v253, 53
	v_readlane_b32 s1, v253, 54
	v_readlane_b32 s2, v253, 0
	v_readlane_b32 s3, v253, 1
	s_mul_i32 s5, s10, 0x2c00000
	s_add_u32 s0, s0, s5
	s_addc_u32 s1, s1, 0
	s_mul_i32 s5, s10, 0x1600000
	s_add_u32 s2, s2, 0x13180000
	s_addc_u32 s3, s3, 0
	s_add_u32 s2, s2, s5
	s_addc_u32 s3, s3, 0
	v_and_b32_e32 v196, 63, v0
	v_lshrrev_b32_e32 v2, 4, v196
	v_and_b32_e32 v208, 15, v196
	v_lshlrev_b32_e32 v208, 4, v208
	s_mul_i32 s12, s11, 0x4100
	v_mul_u32_u24_e32 v209, 0x104, v2
	v_add3_u32 v209, v209, v208, s12
	v_lshl_add_u32 v208, v2, 13, v208
	v_and_b32_e32 v2, 7, v196
	v_lshrrev_b32_e32 v196, 3, v196
	v_mul_u32_u24_e32 v210, 0x820, v2
	v_lshl_add_u32 v210, v196, 2, v210
	v_add_u32_e32 v210, s12, v210
	v_mul_u32_u24_e32 v211, 0x2c00, v196
	v_lshl_add_u32 v211, v2, 4, v211
	s_mov_b32 s13, s4
	s_lshr_b32 s5, s4, 5
	s_and_b32 s6, s4, 31
	s_lshl_b32 s5, s5, 19
	s_lshl_b32 s6, s6, 8
	s_add_u32 s8, s0, s5
	s_addc_u32 s9, s1, 0
	s_add_u32 s8, s8, s6
	s_addc_u32 s9, s9, 0
	global_load_dwordx4 v[4:7], v208, s[8:9] nt
	s_add_u32 s8, s8, 0x8000
	s_addc_u32 s9, s9, 0
	global_load_dwordx4 v[8:11], v208, s[8:9] nt
	s_add_u32 s8, s8, 0x8000
	s_addc_u32 s9, s9, 0
	global_load_dwordx4 v[12:15], v208, s[8:9] nt
	s_add_u32 s8, s8, 0x8000
	s_addc_u32 s9, s9, 0
	global_load_dwordx4 v[16:19], v208, s[8:9] nt
	s_add_u32 s8, s8, 0x8000
	s_addc_u32 s9, s9, 0
	global_load_dwordx4 v[20:23], v208, s[8:9] nt
	s_add_u32 s8, s8, 0x8000
	s_addc_u32 s9, s9, 0
	global_load_dwordx4 v[24:27], v208, s[8:9] nt
	s_add_u32 s8, s8, 0x8000
	s_addc_u32 s9, s9, 0
	global_load_dwordx4 v[28:31], v208, s[8:9] nt
	s_add_u32 s8, s8, 0x8000
	s_addc_u32 s9, s9, 0
	global_load_dwordx4 v[32:35], v208, s[8:9] nt
	s_add_u32 s8, s8, 0x8000
	s_addc_u32 s9, s9, 0
	global_load_dwordx4 v[36:39], v208, s[8:9] nt
	s_add_u32 s8, s8, 0x8000
	s_addc_u32 s9, s9, 0
	global_load_dwordx4 v[40:43], v208, s[8:9] nt
	s_add_u32 s8, s8, 0x8000
	s_addc_u32 s9, s9, 0
	global_load_dwordx4 v[44:47], v208, s[8:9] nt
	s_add_u32 s8, s8, 0x8000
	s_addc_u32 s9, s9, 0
	global_load_dwordx4 v[48:51], v208, s[8:9] nt
	s_add_u32 s8, s8, 0x8000
	s_addc_u32 s9, s9, 0
	global_load_dwordx4 v[52:55], v208, s[8:9] nt
	s_add_u32 s8, s8, 0x8000
	s_addc_u32 s9, s9, 0
	global_load_dwordx4 v[56:59], v208, s[8:9] nt
	s_add_u32 s8, s8, 0x8000
	s_addc_u32 s9, s9, 0
	global_load_dwordx4 v[60:63], v208, s[8:9] nt
	s_add_u32 s8, s8, 0x8000
	s_addc_u32 s9, s9, 0
	global_load_dwordx4 v[64:67], v208, s[8:9] nt
	s_add_i32 s4, s13, 0x400
	s_lshr_b32 s5, s4, 5
	s_and_b32 s6, s4, 31
	s_lshl_b32 s5, s5, 19
	s_lshl_b32 s6, s6, 8
	s_add_u32 s8, s0, s5
	s_addc_u32 s9, s1, 0
	s_add_u32 s8, s8, s6
	s_addc_u32 s9, s9, 0
	global_load_dwordx4 v[68:71], v208, s[8:9] nt
	s_add_u32 s8, s8, 0x8000
	s_addc_u32 s9, s9, 0
	global_load_dwordx4 v[72:75], v208, s[8:9] nt
	s_add_u32 s8, s8, 0x8000
	s_addc_u32 s9, s9, 0
	global_load_dwordx4 v[76:79], v208, s[8:9] nt
	s_add_u32 s8, s8, 0x8000
	s_addc_u32 s9, s9, 0
	global_load_dwordx4 v[80:83], v208, s[8:9] nt
	s_add_u32 s8, s8, 0x8000
	s_addc_u32 s9, s9, 0
	global_load_dwordx4 v[84:87], v208, s[8:9] nt
	s_add_u32 s8, s8, 0x8000
	s_addc_u32 s9, s9, 0
	global_load_dwordx4 v[88:91], v208, s[8:9] nt
	s_add_u32 s8, s8, 0x8000
	s_addc_u32 s9, s9, 0
	global_load_dwordx4 v[92:95], v208, s[8:9] nt
	s_add_u32 s8, s8, 0x8000
	s_addc_u32 s9, s9, 0
	global_load_dwordx4 v[96:99], v208, s[8:9] nt
	s_add_u32 s8, s8, 0x8000
	s_addc_u32 s9, s9, 0
	global_load_dwordx4 v[100:103], v208, s[8:9] nt
	s_add_u32 s8, s8, 0x8000
	s_addc_u32 s9, s9, 0
	global_load_dwordx4 v[104:107], v208, s[8:9] nt
	s_add_u32 s8, s8, 0x8000
	s_addc_u32 s9, s9, 0
	global_load_dwordx4 v[108:111], v208, s[8:9] nt
	s_add_u32 s8, s8, 0x8000
	s_addc_u32 s9, s9, 0
	global_load_dwordx4 v[112:115], v208, s[8:9] nt
	s_add_u32 s8, s8, 0x8000
	s_addc_u32 s9, s9, 0
	global_load_dwordx4 v[116:119], v208, s[8:9] nt
	s_add_u32 s8, s8, 0x8000
	s_addc_u32 s9, s9, 0
	global_load_dwordx4 v[120:123], v208, s[8:9] nt
	s_add_u32 s8, s8, 0x8000
	s_addc_u32 s9, s9, 0
	global_load_dwordx4 v[124:127], v208, s[8:9] nt
	s_add_u32 s8, s8, 0x8000
	s_addc_u32 s9, s9, 0
	global_load_dwordx4 v[128:131], v208, s[8:9] nt
	s_add_i32 s4, s13, 0x800
	s_cmpk_gt_u32 s4, 0xaff
	s_cbranch_scc1 .Lwd_two
	s_lshr_b32 s5, s4, 5
	s_and_b32 s6, s4, 31
	s_lshl_b32 s5, s5, 19
	s_lshl_b32 s6, s6, 8
	s_add_u32 s8, s0, s5
	s_addc_u32 s9, s1, 0
	s_add_u32 s8, s8, s6
	s_addc_u32 s9, s9, 0
	global_load_dwordx4 v[132:135], v208, s[8:9] nt
	s_add_u32 s8, s8, 0x8000
	s_addc_u32 s9, s9, 0
	global_load_dwordx4 v[136:139], v208, s[8:9] nt
	s_add_u32 s8, s8, 0x8000
	s_addc_u32 s9, s9, 0
	global_load_dwordx4 v[140:143], v208, s[8:9] nt
	s_add_u32 s8, s8, 0x8000
	s_addc_u32 s9, s9, 0
	global_load_dwordx4 v[144:147], v208, s[8:9] nt
	s_add_u32 s8, s8, 0x8000
	s_addc_u32 s9, s9, 0
	global_load_dwordx4 v[148:151], v208, s[8:9] nt
	s_add_u32 s8, s8, 0x8000
	s_addc_u32 s9, s9, 0
	global_load_dwordx4 v[152:155], v208, s[8:9] nt
	s_add_u32 s8, s8, 0x8000
	s_addc_u32 s9, s9, 0
	global_load_dwordx4 v[156:159], v208, s[8:9] nt
	s_add_u32 s8, s8, 0x8000
	s_addc_u32 s9, s9, 0
	global_load_dwordx4 v[160:163], v208, s[8:9] nt
	s_add_u32 s8, s8, 0x8000
	s_addc_u32 s9, s9, 0
	global_load_dwordx4 v[164:167], v208, s[8:9] nt
	s_add_u32 s8, s8, 0x8000
	s_addc_u32 s9, s9, 0
	global_load_dwordx4 v[168:171], v208, s[8:9] nt
	s_add_u32 s8, s8, 0x8000
	s_addc_u32 s9, s9, 0
	global_load_dwordx4 v[172:175], v208, s[8:9] nt
	s_add_u32 s8, s8, 0x8000
	s_addc_u32 s9, s9, 0
	global_load_dwordx4 v[176:179], v208, s[8:9] nt
	s_add_u32 s8, s8, 0x8000
	s_addc_u32 s9, s9, 0
	global_load_dwordx4 v[180:183], v208, s[8:9] nt
	s_add_u32 s8, s8, 0x8000
	s_addc_u32 s9, s9, 0
	global_load_dwordx4 v[184:187], v208, s[8:9] nt
	s_add_u32 s8, s8, 0x8000
	s_addc_u32 s9, s9, 0
	global_load_dwordx4 v[188:191], v208, s[8:9] nt
	s_add_u32 s8, s8, 0x8000
	s_addc_u32 s9, s9, 0
	global_load_dwordx4 v[192:195], v208, s[8:9] nt
	s_mov_b32 s4, s13
	s_waitcnt vmcnt(32)
	ds_write_b32 v209, v4 offset:0
	ds_write_b32 v209, v5 offset:4
	ds_write_b32 v209, v6 offset:8
	ds_write_b32 v209, v7 offset:12
	ds_write_b32 v209, v8 offset:1040
	ds_write_b32 v209, v9 offset:1044
	ds_write_b32 v209, v10 offset:1048
	ds_write_b32 v209, v11 offset:1052
	ds_write_b32 v209, v12 offset:2080
	ds_write_b32 v209, v13 offset:2084
	ds_write_b32 v209, v14 offset:2088
	ds_write_b32 v209, v15 offset:2092
	ds_write_b32 v209, v16 offset:3120
	ds_write_b32 v209, v17 offset:3124
	ds_write_b32 v209, v18 offset:3128
	ds_write_b32 v209, v19 offset:3132
	ds_write_b32 v209, v20 offset:4160
	ds_write_b32 v209, v21 offset:4164
	ds_write_b32 v209, v22 offset:4168
	ds_write_b32 v209, v23 offset:4172
	ds_write_b32 v209, v24 offset:5200
	ds_write_b32 v209, v25 offset:5204
	ds_write_b32 v209, v26 offset:5208
	ds_write_b32 v209, v27 offset:5212
	ds_write_b32 v209, v28 offset:6240
	ds_write_b32 v209, v29 offset:6244
	ds_write_b32 v209, v30 offset:6248
	ds_write_b32 v209, v31 offset:6252
	ds_write_b32 v209, v32 offset:7280
	ds_write_b32 v209, v33 offset:7284
	ds_write_b32 v209, v34 offset:7288
	ds_write_b32 v209, v35 offset:7292
	ds_write_b32 v209, v36 offset:8320
	ds_write_b32 v209, v37 offset:8324
	ds_write_b32 v209, v38 offset:8328
	ds_write_b32 v209, v39 offset:8332
	ds_write_b32 v209, v40 offset:9360
	ds_write_b32 v209, v41 offset:9364
	ds_write_b32 v209, v42 offset:9368
	ds_write_b32 v209, v43 offset:9372
	ds_write_b32 v209, v44 offset:10400
	ds_write_b32 v209, v45 offset:10404
	ds_write_b32 v209, v46 offset:10408
	ds_write_b32 v209, v47 offset:10412
	ds_write_b32 v209, v48 offset:11440
	ds_write_b32 v209, v49 offset:11444
	ds_write_b32 v209, v50 offset:11448
	ds_write_b32 v209, v51 offset:11452
	ds_write_b32 v209, v52 offset:12480
	ds_write_b32 v209, v53 offset:12484
	ds_write_b32 v209, v54 offset:12488
	ds_write_b32 v209, v55 offset:12492
	ds_write_b32 v209, v56 offset:13520
	ds_write_b32 v209, v57 offset:13524
	ds_write_b32 v209, v58 offset:13528
	ds_write_b32 v209, v59 offset:13532
	ds_write_b32 v209, v60 offset:14560
	ds_write_b32 v209, v61 offset:14564
	ds_write_b32 v209, v62 offset:14568
	ds_write_b32 v209, v63 offset:14572
	ds_write_b32 v209, v64 offset:15600
	ds_write_b32 v209, v65 offset:15604
	ds_write_b32 v209, v66 offset:15608
	ds_write_b32 v209, v67 offset:15612
	s_lshr_b32 s5, s4, 5
	s_and_b32 s6, s4, 31
	s_mul_i32 s6, s6, 0xb0000
	s_lshl_b32 s5, s5, 7
	s_add_u32 s8, s2, s6
	s_addc_u32 s9, s3, 0
	s_add_u32 s8, s8, s5
	s_addc_u32 s9, s9, 0
	s_waitcnt lgkmcnt(0)
	ds_read_b32 v196, v210 offset:0
	ds_read_b32 v197, v210 offset:260
	ds_read_b32 v198, v210 offset:520
	ds_read_b32 v199, v210 offset:780
	ds_read_b32 v200, v210 offset:1040
	ds_read_b32 v201, v210 offset:1300
	ds_read_b32 v202, v210 offset:1560
	ds_read_b32 v203, v210 offset:1820
	s_waitcnt lgkmcnt(0)
	v_cvt_pk_bf16_f32 v204, v196, v197
	v_cvt_pk_bf16_f32 v205, v198, v199
	v_cvt_pk_bf16_f32 v206, v200, v201
	v_cvt_pk_bf16_f32 v207, v202, v203
	global_store_dwordx4 v211, v[204:207], s[8:9] nt
	s_add_u32 s8, s8, 0x16000
	s_addc_u32 s9, s9, 0
	s_nop 1
	ds_read_b32 v196, v210 offset:32
	ds_read_b32 v197, v210 offset:292
	ds_read_b32 v198, v210 offset:552
	ds_read_b32 v199, v210 offset:812
	ds_read_b32 v200, v210 offset:1072
	ds_read_b32 v201, v210 offset:1332
	ds_read_b32 v202, v210 offset:1592
	ds_read_b32 v203, v210 offset:1852
	s_waitcnt lgkmcnt(0)
	v_cvt_pk_bf16_f32 v204, v196, v197
	v_cvt_pk_bf16_f32 v205, v198, v199
	v_cvt_pk_bf16_f32 v206, v200, v201
	v_cvt_pk_bf16_f32 v207, v202, v203
	global_store_dwordx4 v211, v[204:207], s[8:9] nt
	s_add_u32 s8, s8, 0x16000
	s_addc_u32 s9, s9, 0
	s_nop 1
	ds_read_b32 v196, v210 offset:64
	ds_read_b32 v197, v210 offset:324
	ds_read_b32 v198, v210 offset:584
	ds_read_b32 v199, v210 offset:844
	ds_read_b32 v200, v210 offset:1104
	ds_read_b32 v201, v210 offset:1364
	ds_read_b32 v202, v210 offset:1624
	ds_read_b32 v203, v210 offset:1884
	s_waitcnt lgkmcnt(0)
	v_cvt_pk_bf16_f32 v204, v196, v197
	v_cvt_pk_bf16_f32 v205, v198, v199
	v_cvt_pk_bf16_f32 v206, v200, v201
	v_cvt_pk_bf16_f32 v207, v202, v203
	global_store_dwordx4 v211, v[204:207], s[8:9] nt
	s_add_u32 s8, s8, 0x16000
	s_addc_u32 s9, s9, 0
	s_nop 1
	ds_read_b32 v196, v210 offset:96
	ds_read_b32 v197, v210 offset:356
	ds_read_b32 v198, v210 offset:616
	ds_read_b32 v199, v210 offset:876
	ds_read_b32 v200, v210 offset:1136
	ds_read_b32 v201, v210 offset:1396
	ds_read_b32 v202, v210 offset:1656
	ds_read_b32 v203, v210 offset:1916
	s_waitcnt lgkmcnt(0)
	v_cvt_pk_bf16_f32 v204, v196, v197
	v_cvt_pk_bf16_f32 v205, v198, v199
	v_cvt_pk_bf16_f32 v206, v200, v201
	v_cvt_pk_bf16_f32 v207, v202, v203
	global_store_dwordx4 v211, v[204:207], s[8:9] nt
	s_add_u32 s8, s8, 0x16000
	s_addc_u32 s9, s9, 0
	s_nop 1
	ds_read_b32 v196, v210 offset:128
	ds_read_b32 v197, v210 offset:388
	ds_read_b32 v198, v210 offset:648
	ds_read_b32 v199, v210 offset:908
	ds_read_b32 v200, v210 offset:1168
	ds_read_b32 v201, v210 offset:1428
	ds_read_b32 v202, v210 offset:1688
	ds_read_b32 v203, v210 offset:1948
	s_waitcnt lgkmcnt(0)
	v_cvt_pk_bf16_f32 v204, v196, v197
	v_cvt_pk_bf16_f32 v205, v198, v199
	v_cvt_pk_bf16_f32 v206, v200, v201
	v_cvt_pk_bf16_f32 v207, v202, v203
	global_store_dwordx4 v211, v[204:207], s[8:9] nt
	s_add_u32 s8, s8, 0x16000
	s_addc_u32 s9, s9, 0
	s_nop 1
	ds_read_b32 v196, v210 offset:160
	ds_read_b32 v197, v210 offset:420
	ds_read_b32 v198, v210 offset:680
	ds_read_b32 v199, v210 offset:940
	ds_read_b32 v200, v210 offset:1200
	ds_read_b32 v201, v210 offset:1460
	ds_read_b32 v202, v210 offset:1720
	ds_read_b32 v203, v210 offset:1980
	s_waitcnt lgkmcnt(0)
	v_cvt_pk_bf16_f32 v204, v196, v197
	v_cvt_pk_bf16_f32 v205, v198, v199
	v_cvt_pk_bf16_f32 v206, v200, v201
	v_cvt_pk_bf16_f32 v207, v202, v203
	global_store_dwordx4 v211, v[204:207], s[8:9] nt
	s_add_u32 s8, s8, 0x16000
	s_addc_u32 s9, s9, 0
	s_nop 1
	ds_read_b32 v196, v210 offset:192
	ds_read_b32 v197, v210 offset:452
	ds_read_b32 v198, v210 offset:712
	ds_read_b32 v199, v210 offset:972
	ds_read_b32 v200, v210 offset:1232
	ds_read_b32 v201, v210 offset:1492
	ds_read_b32 v202, v210 offset:1752
	ds_read_b32 v203, v210 offset:2012
	s_waitcnt lgkmcnt(0)
	v_cvt_pk_bf16_f32 v204, v196, v197
	v_cvt_pk_bf16_f32 v205, v198, v199
	v_cvt_pk_bf16_f32 v206, v200, v201
	v_cvt_pk_bf16_f32 v207, v202, v203
	global_store_dwordx4 v211, v[204:207], s[8:9] nt
	s_add_u32 s8, s8, 0x16000
	s_addc_u32 s9, s9, 0
	s_nop 1
	ds_read_b32 v196, v210 offset:224
	ds_read_b32 v197, v210 offset:484
	ds_read_b32 v198, v210 offset:744
	ds_read_b32 v199, v210 offset:1004
	ds_read_b32 v200, v210 offset:1264
	ds_read_b32 v201, v210 offset:1524
	ds_read_b32 v202, v210 offset:1784
	ds_read_b32 v203, v210 offset:2044
	s_waitcnt lgkmcnt(0)
	v_cvt_pk_bf16_f32 v204, v196, v197
	v_cvt_pk_bf16_f32 v205, v198, v199
	v_cvt_pk_bf16_f32 v206, v200, v201
	v_cvt_pk_bf16_f32 v207, v202, v203
	global_store_dwordx4 v211, v[204:207], s[8:9] nt
	s_nop 1
	s_add_i32 s4, s13, 0x400
	s_waitcnt vmcnt(16)
	ds_write_b32 v209, v68 offset:0
	ds_write_b32 v209, v69 offset:4
	ds_write_b32 v209, v70 offset:8
	ds_write_b32 v209, v71 offset:12
	ds_write_b32 v209, v72 offset:1040
	ds_write_b32 v209, v73 offset:1044
	ds_write_b32 v209, v74 offset:1048
	ds_write_b32 v209, v75 offset:1052
	ds_write_b32 v209, v76 offset:2080
	ds_write_b32 v209, v77 offset:2084
	ds_write_b32 v209, v78 offset:2088
	ds_write_b32 v209, v79 offset:2092
	ds_write_b32 v209, v80 offset:3120
	ds_write_b32 v209, v81 offset:3124
	ds_write_b32 v209, v82 offset:3128
	ds_write_b32 v209, v83 offset:3132
	ds_write_b32 v209, v84 offset:4160
	ds_write_b32 v209, v85 offset:4164
	ds_write_b32 v209, v86 offset:4168
	ds_write_b32 v209, v87 offset:4172
	ds_write_b32 v209, v88 offset:5200
	ds_write_b32 v209, v89 offset:5204
	ds_write_b32 v209, v90 offset:5208
	ds_write_b32 v209, v91 offset:5212
	ds_write_b32 v209, v92 offset:6240
	ds_write_b32 v209, v93 offset:6244
	ds_write_b32 v209, v94 offset:6248
	ds_write_b32 v209, v95 offset:6252
	ds_write_b32 v209, v96 offset:7280
	ds_write_b32 v209, v97 offset:7284
	ds_write_b32 v209, v98 offset:7288
	ds_write_b32 v209, v99 offset:7292
	ds_write_b32 v209, v100 offset:8320
	ds_write_b32 v209, v101 offset:8324
	ds_write_b32 v209, v102 offset:8328
	ds_write_b32 v209, v103 offset:8332
	ds_write_b32 v209, v104 offset:9360
	ds_write_b32 v209, v105 offset:9364
	ds_write_b32 v209, v106 offset:9368
	ds_write_b32 v209, v107 offset:9372
	ds_write_b32 v209, v108 offset:10400
	ds_write_b32 v209, v109 offset:10404
	ds_write_b32 v209, v110 offset:10408
	ds_write_b32 v209, v111 offset:10412
	ds_write_b32 v209, v112 offset:11440
	ds_write_b32 v209, v113 offset:11444
	ds_write_b32 v209, v114 offset:11448
	ds_write_b32 v209, v115 offset:11452
	ds_write_b32 v209, v116 offset:12480
	ds_write_b32 v209, v117 offset:12484
	ds_write_b32 v209, v118 offset:12488
	ds_write_b32 v209, v119 offset:12492
	ds_write_b32 v209, v120 offset:13520
	ds_write_b32 v209, v121 offset:13524
	ds_write_b32 v209, v122 offset:13528
	ds_write_b32 v209, v123 offset:13532
	ds_write_b32 v209, v124 offset:14560
	ds_write_b32 v209, v125 offset:14564
	ds_write_b32 v209, v126 offset:14568
	ds_write_b32 v209, v127 offset:14572
	ds_write_b32 v209, v128 offset:15600
	ds_write_b32 v209, v129 offset:15604
	ds_write_b32 v209, v130 offset:15608
	ds_write_b32 v209, v131 offset:15612
	s_lshr_b32 s5, s4, 5
	s_and_b32 s6, s4, 31
	s_mul_i32 s6, s6, 0xb0000
	s_lshl_b32 s5, s5, 7
	s_add_u32 s8, s2, s6
	s_addc_u32 s9, s3, 0
	s_add_u32 s8, s8, s5
	s_addc_u32 s9, s9, 0
	s_waitcnt lgkmcnt(0)
	ds_read_b32 v196, v210 offset:0
	ds_read_b32 v197, v210 offset:260
	ds_read_b32 v198, v210 offset:520
	ds_read_b32 v199, v210 offset:780
	ds_read_b32 v200, v210 offset:1040
	ds_read_b32 v201, v210 offset:1300
	ds_read_b32 v202, v210 offset:1560
	ds_read_b32 v203, v210 offset:1820
	s_waitcnt lgkmcnt(0)
	v_cvt_pk_bf16_f32 v204, v196, v197
	v_cvt_pk_bf16_f32 v205, v198, v199
	v_cvt_pk_bf16_f32 v206, v200, v201
	v_cvt_pk_bf16_f32 v207, v202, v203
	global_store_dwordx4 v211, v[204:207], s[8:9] nt
	s_add_u32 s8, s8, 0x16000
	s_addc_u32 s9, s9, 0
	s_nop 1
	ds_read_b32 v196, v210 offset:32
	ds_read_b32 v197, v210 offset:292
	ds_read_b32 v198, v210 offset:552
	ds_read_b32 v199, v210 offset:812
	ds_read_b32 v200, v210 offset:1072
	ds_read_b32 v201, v210 offset:1332
	ds_read_b32 v202, v210 offset:1592
	ds_read_b32 v203, v210 offset:1852
	s_waitcnt lgkmcnt(0)
	v_cvt_pk_bf16_f32 v204, v196, v197
	v_cvt_pk_bf16_f32 v205, v198, v199
	v_cvt_pk_bf16_f32 v206, v200, v201
	v_cvt_pk_bf16_f32 v207, v202, v203
	global_store_dwordx4 v211, v[204:207], s[8:9] nt
	s_add_u32 s8, s8, 0x16000
	s_addc_u32 s9, s9, 0
	s_nop 1
	ds_read_b32 v196, v210 offset:64
	ds_read_b32 v197, v210 offset:324
	ds_read_b32 v198, v210 offset:584
	ds_read_b32 v199, v210 offset:844
	ds_read_b32 v200, v210 offset:1104
	ds_read_b32 v201, v210 offset:1364
	ds_read_b32 v202, v210 offset:1624
	ds_read_b32 v203, v210 offset:1884
	s_waitcnt lgkmcnt(0)
	v_cvt_pk_bf16_f32 v204, v196, v197
	v_cvt_pk_bf16_f32 v205, v198, v199
	v_cvt_pk_bf16_f32 v206, v200, v201
	v_cvt_pk_bf16_f32 v207, v202, v203
	global_store_dwordx4 v211, v[204:207], s[8:9] nt
	s_add_u32 s8, s8, 0x16000
	s_addc_u32 s9, s9, 0
	s_nop 1
	ds_read_b32 v196, v210 offset:96
	ds_read_b32 v197, v210 offset:356
	ds_read_b32 v198, v210 offset:616
	ds_read_b32 v199, v210 offset:876
	ds_read_b32 v200, v210 offset:1136
	ds_read_b32 v201, v210 offset:1396
	ds_read_b32 v202, v210 offset:1656
	ds_read_b32 v203, v210 offset:1916
	s_waitcnt lgkmcnt(0)
	v_cvt_pk_bf16_f32 v204, v196, v197
	v_cvt_pk_bf16_f32 v205, v198, v199
	v_cvt_pk_bf16_f32 v206, v200, v201
	v_cvt_pk_bf16_f32 v207, v202, v203
	global_store_dwordx4 v211, v[204:207], s[8:9] nt
	s_add_u32 s8, s8, 0x16000
	s_addc_u32 s9, s9, 0
	s_nop 1
	ds_read_b32 v196, v210 offset:128
	ds_read_b32 v197, v210 offset:388
	ds_read_b32 v198, v210 offset:648
	ds_read_b32 v199, v210 offset:908
	ds_read_b32 v200, v210 offset:1168
	ds_read_b32 v201, v210 offset:1428
	ds_read_b32 v202, v210 offset:1688
	ds_read_b32 v203, v210 offset:1948
	s_waitcnt lgkmcnt(0)
	v_cvt_pk_bf16_f32 v204, v196, v197
	v_cvt_pk_bf16_f32 v205, v198, v199
	v_cvt_pk_bf16_f32 v206, v200, v201
	v_cvt_pk_bf16_f32 v207, v202, v203
	global_store_dwordx4 v211, v[204:207], s[8:9] nt
	s_add_u32 s8, s8, 0x16000
	s_addc_u32 s9, s9, 0
	s_nop 1
	ds_read_b32 v196, v210 offset:160
	ds_read_b32 v197, v210 offset:420
	ds_read_b32 v198, v210 offset:680
	ds_read_b32 v199, v210 offset:940
	ds_read_b32 v200, v210 offset:1200
	ds_read_b32 v201, v210 offset:1460
	ds_read_b32 v202, v210 offset:1720
	ds_read_b32 v203, v210 offset:1980
	s_waitcnt lgkmcnt(0)
	v_cvt_pk_bf16_f32 v204, v196, v197
	v_cvt_pk_bf16_f32 v205, v198, v199
	v_cvt_pk_bf16_f32 v206, v200, v201
	v_cvt_pk_bf16_f32 v207, v202, v203
	global_store_dwordx4 v211, v[204:207], s[8:9] nt
	s_add_u32 s8, s8, 0x16000
	s_addc_u32 s9, s9, 0
	s_nop 1
	ds_read_b32 v196, v210 offset:192
	ds_read_b32 v197, v210 offset:452
	ds_read_b32 v198, v210 offset:712
	ds_read_b32 v199, v210 offset:972
	ds_read_b32 v200, v210 offset:1232
	ds_read_b32 v201, v210 offset:1492
	ds_read_b32 v202, v210 offset:1752
	ds_read_b32 v203, v210 offset:2012
	s_waitcnt lgkmcnt(0)
	v_cvt_pk_bf16_f32 v204, v196, v197
	v_cvt_pk_bf16_f32 v205, v198, v199
	v_cvt_pk_bf16_f32 v206, v200, v201
	v_cvt_pk_bf16_f32 v207, v202, v203
	global_store_dwordx4 v211, v[204:207], s[8:9] nt
	s_add_u32 s8, s8, 0x16000
	s_addc_u32 s9, s9, 0
	s_nop 1
	ds_read_b32 v196, v210 offset:224
	ds_read_b32 v197, v210 offset:484
	ds_read_b32 v198, v210 offset:744
	ds_read_b32 v199, v210 offset:1004
	ds_read_b32 v200, v210 offset:1264
	ds_read_b32 v201, v210 offset:1524
	ds_read_b32 v202, v210 offset:1784
	ds_read_b32 v203, v210 offset:2044
	s_waitcnt lgkmcnt(0)
	v_cvt_pk_bf16_f32 v204, v196, v197
	v_cvt_pk_bf16_f32 v205, v198, v199
	v_cvt_pk_bf16_f32 v206, v200, v201
	v_cvt_pk_bf16_f32 v207, v202, v203
	global_store_dwordx4 v211, v[204:207], s[8:9] nt
	s_nop 1
	s_add_i32 s4, s13, 0x800
	s_waitcnt vmcnt(0)
	ds_write_b32 v209, v132 offset:0
	ds_write_b32 v209, v133 offset:4
	ds_write_b32 v209, v134 offset:8
	ds_write_b32 v209, v135 offset:12
	ds_write_b32 v209, v136 offset:1040
	ds_write_b32 v209, v137 offset:1044
	ds_write_b32 v209, v138 offset:1048
	ds_write_b32 v209, v139 offset:1052
	ds_write_b32 v209, v140 offset:2080
	ds_write_b32 v209, v141 offset:2084
	ds_write_b32 v209, v142 offset:2088
	ds_write_b32 v209, v143 offset:2092
	ds_write_b32 v209, v144 offset:3120
	ds_write_b32 v209, v145 offset:3124
	ds_write_b32 v209, v146 offset:3128
	ds_write_b32 v209, v147 offset:3132
	ds_write_b32 v209, v148 offset:4160
	ds_write_b32 v209, v149 offset:4164
	ds_write_b32 v209, v150 offset:4168
	ds_write_b32 v209, v151 offset:4172
	ds_write_b32 v209, v152 offset:5200
	ds_write_b32 v209, v153 offset:5204
	ds_write_b32 v209, v154 offset:5208
	ds_write_b32 v209, v155 offset:5212
	ds_write_b32 v209, v156 offset:6240
	ds_write_b32 v209, v157 offset:6244
	ds_write_b32 v209, v158 offset:6248
	ds_write_b32 v209, v159 offset:6252
	ds_write_b32 v209, v160 offset:7280
	ds_write_b32 v209, v161 offset:7284
	ds_write_b32 v209, v162 offset:7288
	ds_write_b32 v209, v163 offset:7292
	ds_write_b32 v209, v164 offset:8320
	ds_write_b32 v209, v165 offset:8324
	ds_write_b32 v209, v166 offset:8328
	ds_write_b32 v209, v167 offset:8332
	ds_write_b32 v209, v168 offset:9360
	ds_write_b32 v209, v169 offset:9364
	ds_write_b32 v209, v170 offset:9368
	ds_write_b32 v209, v171 offset:9372
	ds_write_b32 v209, v172 offset:10400
	ds_write_b32 v209, v173 offset:10404
	ds_write_b32 v209, v174 offset:10408
	ds_write_b32 v209, v175 offset:10412
	ds_write_b32 v209, v176 offset:11440
	ds_write_b32 v209, v177 offset:11444
	ds_write_b32 v209, v178 offset:11448
	ds_write_b32 v209, v179 offset:11452
	ds_write_b32 v209, v180 offset:12480
	ds_write_b32 v209, v181 offset:12484
	ds_write_b32 v209, v182 offset:12488
	ds_write_b32 v209, v183 offset:12492
	ds_write_b32 v209, v184 offset:13520
	ds_write_b32 v209, v185 offset:13524
	ds_write_b32 v209, v186 offset:13528
	ds_write_b32 v209, v187 offset:13532
	ds_write_b32 v209, v188 offset:14560
	ds_write_b32 v209, v189 offset:14564
	ds_write_b32 v209, v190 offset:14568
	ds_write_b32 v209, v191 offset:14572
	ds_write_b32 v209, v192 offset:15600
	ds_write_b32 v209, v193 offset:15604
	ds_write_b32 v209, v194 offset:15608
	ds_write_b32 v209, v195 offset:15612
	s_lshr_b32 s5, s4, 5
	s_and_b32 s6, s4, 31
	s_mul_i32 s6, s6, 0xb0000
	s_lshl_b32 s5, s5, 7
	s_add_u32 s8, s2, s6
	s_addc_u32 s9, s3, 0
	s_add_u32 s8, s8, s5
	s_addc_u32 s9, s9, 0
	s_waitcnt lgkmcnt(0)
	ds_read_b32 v196, v210 offset:0
	ds_read_b32 v197, v210 offset:260
	ds_read_b32 v198, v210 offset:520
	ds_read_b32 v199, v210 offset:780
	ds_read_b32 v200, v210 offset:1040
	ds_read_b32 v201, v210 offset:1300
	ds_read_b32 v202, v210 offset:1560
	ds_read_b32 v203, v210 offset:1820
	s_waitcnt lgkmcnt(0)
	v_cvt_pk_bf16_f32 v204, v196, v197
	v_cvt_pk_bf16_f32 v205, v198, v199
	v_cvt_pk_bf16_f32 v206, v200, v201
	v_cvt_pk_bf16_f32 v207, v202, v203
	global_store_dwordx4 v211, v[204:207], s[8:9] nt
	s_add_u32 s8, s8, 0x16000
	s_addc_u32 s9, s9, 0
	s_nop 1
	ds_read_b32 v196, v210 offset:32
	ds_read_b32 v197, v210 offset:292
	ds_read_b32 v198, v210 offset:552
	ds_read_b32 v199, v210 offset:812
	ds_read_b32 v200, v210 offset:1072
	ds_read_b32 v201, v210 offset:1332
	ds_read_b32 v202, v210 offset:1592
	ds_read_b32 v203, v210 offset:1852
	s_waitcnt lgkmcnt(0)
	v_cvt_pk_bf16_f32 v204, v196, v197
	v_cvt_pk_bf16_f32 v205, v198, v199
	v_cvt_pk_bf16_f32 v206, v200, v201
	v_cvt_pk_bf16_f32 v207, v202, v203
	global_store_dwordx4 v211, v[204:207], s[8:9] nt
	s_add_u32 s8, s8, 0x16000
	s_addc_u32 s9, s9, 0
	s_nop 1
	ds_read_b32 v196, v210 offset:64
	ds_read_b32 v197, v210 offset:324
	ds_read_b32 v198, v210 offset:584
	ds_read_b32 v199, v210 offset:844
	ds_read_b32 v200, v210 offset:1104
	ds_read_b32 v201, v210 offset:1364
	ds_read_b32 v202, v210 offset:1624
	ds_read_b32 v203, v210 offset:1884
	s_waitcnt lgkmcnt(0)
	v_cvt_pk_bf16_f32 v204, v196, v197
	v_cvt_pk_bf16_f32 v205, v198, v199
	v_cvt_pk_bf16_f32 v206, v200, v201
	v_cvt_pk_bf16_f32 v207, v202, v203
	global_store_dwordx4 v211, v[204:207], s[8:9] nt
	s_add_u32 s8, s8, 0x16000
	s_addc_u32 s9, s9, 0
	s_nop 1
	ds_read_b32 v196, v210 offset:96
	ds_read_b32 v197, v210 offset:356
	ds_read_b32 v198, v210 offset:616
	ds_read_b32 v199, v210 offset:876
	ds_read_b32 v200, v210 offset:1136
	ds_read_b32 v201, v210 offset:1396
	ds_read_b32 v202, v210 offset:1656
	ds_read_b32 v203, v210 offset:1916
	s_waitcnt lgkmcnt(0)
	v_cvt_pk_bf16_f32 v204, v196, v197
	v_cvt_pk_bf16_f32 v205, v198, v199
	v_cvt_pk_bf16_f32 v206, v200, v201
	v_cvt_pk_bf16_f32 v207, v202, v203
	global_store_dwordx4 v211, v[204:207], s[8:9] nt
	s_add_u32 s8, s8, 0x16000
	s_addc_u32 s9, s9, 0
	s_nop 1
	ds_read_b32 v196, v210 offset:128
	ds_read_b32 v197, v210 offset:388
	ds_read_b32 v198, v210 offset:648
	ds_read_b32 v199, v210 offset:908
	ds_read_b32 v200, v210 offset:1168
	ds_read_b32 v201, v210 offset:1428
	ds_read_b32 v202, v210 offset:1688
	ds_read_b32 v203, v210 offset:1948
	s_waitcnt lgkmcnt(0)
	v_cvt_pk_bf16_f32 v204, v196, v197
	v_cvt_pk_bf16_f32 v205, v198, v199
	v_cvt_pk_bf16_f32 v206, v200, v201
	v_cvt_pk_bf16_f32 v207, v202, v203
	global_store_dwordx4 v211, v[204:207], s[8:9] nt
	s_add_u32 s8, s8, 0x16000
	s_addc_u32 s9, s9, 0
	s_nop 1
	ds_read_b32 v196, v210 offset:160
	ds_read_b32 v197, v210 offset:420
	ds_read_b32 v198, v210 offset:680
	ds_read_b32 v199, v210 offset:940
	ds_read_b32 v200, v210 offset:1200
	ds_read_b32 v201, v210 offset:1460
	ds_read_b32 v202, v210 offset:1720
	ds_read_b32 v203, v210 offset:1980
	s_waitcnt lgkmcnt(0)
	v_cvt_pk_bf16_f32 v204, v196, v197
	v_cvt_pk_bf16_f32 v205, v198, v199
	v_cvt_pk_bf16_f32 v206, v200, v201
	v_cvt_pk_bf16_f32 v207, v202, v203
	global_store_dwordx4 v211, v[204:207], s[8:9] nt
	s_add_u32 s8, s8, 0x16000
	s_addc_u32 s9, s9, 0
	s_nop 1
	ds_read_b32 v196, v210 offset:192
	ds_read_b32 v197, v210 offset:452
	ds_read_b32 v198, v210 offset:712
	ds_read_b32 v199, v210 offset:972
	ds_read_b32 v200, v210 offset:1232
	ds_read_b32 v201, v210 offset:1492
	ds_read_b32 v202, v210 offset:1752
	ds_read_b32 v203, v210 offset:2012
	s_waitcnt lgkmcnt(0)
	v_cvt_pk_bf16_f32 v204, v196, v197
	v_cvt_pk_bf16_f32 v205, v198, v199
	v_cvt_pk_bf16_f32 v206, v200, v201
	v_cvt_pk_bf16_f32 v207, v202, v203
	global_store_dwordx4 v211, v[204:207], s[8:9] nt
	s_add_u32 s8, s8, 0x16000
	s_addc_u32 s9, s9, 0
	s_nop 1
	ds_read_b32 v196, v210 offset:224
	ds_read_b32 v197, v210 offset:484
	ds_read_b32 v198, v210 offset:744
	ds_read_b32 v199, v210 offset:1004
	ds_read_b32 v200, v210 offset:1264
	ds_read_b32 v201, v210 offset:1524
	ds_read_b32 v202, v210 offset:1784
	ds_read_b32 v203, v210 offset:2044
	s_waitcnt lgkmcnt(0)
	v_cvt_pk_bf16_f32 v204, v196, v197
	v_cvt_pk_bf16_f32 v205, v198, v199
	v_cvt_pk_bf16_f32 v206, v200, v201
	v_cvt_pk_bf16_f32 v207, v202, v203
	global_store_dwordx4 v211, v[204:207], s[8:9] nt
	s_nop 1
	s_branch .Lwd_fin
.Lwd_two:
	s_mov_b32 s4, s13
	s_waitcnt vmcnt(16)
	ds_write_b32 v209, v4 offset:0
	ds_write_b32 v209, v5 offset:4
	ds_write_b32 v209, v6 offset:8
	ds_write_b32 v209, v7 offset:12
	ds_write_b32 v209, v8 offset:1040
	ds_write_b32 v209, v9 offset:1044
	ds_write_b32 v209, v10 offset:1048
	ds_write_b32 v209, v11 offset:1052
	ds_write_b32 v209, v12 offset:2080
	ds_write_b32 v209, v13 offset:2084
	ds_write_b32 v209, v14 offset:2088
	ds_write_b32 v209, v15 offset:2092
	ds_write_b32 v209, v16 offset:3120
	ds_write_b32 v209, v17 offset:3124
	ds_write_b32 v209, v18 offset:3128
	ds_write_b32 v209, v19 offset:3132
	ds_write_b32 v209, v20 offset:4160
	ds_write_b32 v209, v21 offset:4164
	ds_write_b32 v209, v22 offset:4168
	ds_write_b32 v209, v23 offset:4172
	ds_write_b32 v209, v24 offset:5200
	ds_write_b32 v209, v25 offset:5204
	ds_write_b32 v209, v26 offset:5208
	ds_write_b32 v209, v27 offset:5212
	ds_write_b32 v209, v28 offset:6240
	ds_write_b32 v209, v29 offset:6244
	ds_write_b32 v209, v30 offset:6248
	ds_write_b32 v209, v31 offset:6252
	ds_write_b32 v209, v32 offset:7280
	ds_write_b32 v209, v33 offset:7284
	ds_write_b32 v209, v34 offset:7288
	ds_write_b32 v209, v35 offset:7292
	ds_write_b32 v209, v36 offset:8320
	ds_write_b32 v209, v37 offset:8324
	ds_write_b32 v209, v38 offset:8328
	ds_write_b32 v209, v39 offset:8332
	ds_write_b32 v209, v40 offset:9360
	ds_write_b32 v209, v41 offset:9364
	ds_write_b32 v209, v42 offset:9368
	ds_write_b32 v209, v43 offset:9372
	ds_write_b32 v209, v44 offset:10400
	ds_write_b32 v209, v45 offset:10404
	ds_write_b32 v209, v46 offset:10408
	ds_write_b32 v209, v47 offset:10412
	ds_write_b32 v209, v48 offset:11440
	ds_write_b32 v209, v49 offset:11444
	ds_write_b32 v209, v50 offset:11448
	ds_write_b32 v209, v51 offset:11452
	ds_write_b32 v209, v52 offset:12480
	ds_write_b32 v209, v53 offset:12484
	ds_write_b32 v209, v54 offset:12488
	ds_write_b32 v209, v55 offset:12492
	ds_write_b32 v209, v56 offset:13520
	ds_write_b32 v209, v57 offset:13524
	ds_write_b32 v209, v58 offset:13528
	ds_write_b32 v209, v59 offset:13532
	ds_write_b32 v209, v60 offset:14560
	ds_write_b32 v209, v61 offset:14564
	ds_write_b32 v209, v62 offset:14568
	ds_write_b32 v209, v63 offset:14572
	ds_write_b32 v209, v64 offset:15600
	ds_write_b32 v209, v65 offset:15604
	ds_write_b32 v209, v66 offset:15608
	ds_write_b32 v209, v67 offset:15612
	s_lshr_b32 s5, s4, 5
	s_and_b32 s6, s4, 31
	s_mul_i32 s6, s6, 0xb0000
	s_lshl_b32 s5, s5, 7
	s_add_u32 s8, s2, s6
	s_addc_u32 s9, s3, 0
	s_add_u32 s8, s8, s5
	s_addc_u32 s9, s9, 0
	s_waitcnt lgkmcnt(0)
	ds_read_b32 v196, v210 offset:0
	ds_read_b32 v197, v210 offset:260
	ds_read_b32 v198, v210 offset:520
	ds_read_b32 v199, v210 offset:780
	ds_read_b32 v200, v210 offset:1040
	ds_read_b32 v201, v210 offset:1300
	ds_read_b32 v202, v210 offset:1560
	ds_read_b32 v203, v210 offset:1820
	s_waitcnt lgkmcnt(0)
	v_cvt_pk_bf16_f32 v204, v196, v197
	v_cvt_pk_bf16_f32 v205, v198, v199
	v_cvt_pk_bf16_f32 v206, v200, v201
	v_cvt_pk_bf16_f32 v207, v202, v203
	global_store_dwordx4 v211, v[204:207], s[8:9] nt
	s_add_u32 s8, s8, 0x16000
	s_addc_u32 s9, s9, 0
	s_nop 1
	ds_read_b32 v196, v210 offset:32
	ds_read_b32 v197, v210 offset:292
	ds_read_b32 v198, v210 offset:552
	ds_read_b32 v199, v210 offset:812
	ds_read_b32 v200, v210 offset:1072
	ds_read_b32 v201, v210 offset:1332
	ds_read_b32 v202, v210 offset:1592
	ds_read_b32 v203, v210 offset:1852
	s_waitcnt lgkmcnt(0)
	v_cvt_pk_bf16_f32 v204, v196, v197
	v_cvt_pk_bf16_f32 v205, v198, v199
	v_cvt_pk_bf16_f32 v206, v200, v201
	v_cvt_pk_bf16_f32 v207, v202, v203
	global_store_dwordx4 v211, v[204:207], s[8:9] nt
	s_add_u32 s8, s8, 0x16000
	s_addc_u32 s9, s9, 0
	s_nop 1
	ds_read_b32 v196, v210 offset:64
	ds_read_b32 v197, v210 offset:324
	ds_read_b32 v198, v210 offset:584
	ds_read_b32 v199, v210 offset:844
	ds_read_b32 v200, v210 offset:1104
	ds_read_b32 v201, v210 offset:1364
	ds_read_b32 v202, v210 offset:1624
	ds_read_b32 v203, v210 offset:1884
	s_waitcnt lgkmcnt(0)
	v_cvt_pk_bf16_f32 v204, v196, v197
	v_cvt_pk_bf16_f32 v205, v198, v199
	v_cvt_pk_bf16_f32 v206, v200, v201
	v_cvt_pk_bf16_f32 v207, v202, v203
	global_store_dwordx4 v211, v[204:207], s[8:9] nt
	s_add_u32 s8, s8, 0x16000
	s_addc_u32 s9, s9, 0
	s_nop 1
	ds_read_b32 v196, v210 offset:96
	ds_read_b32 v197, v210 offset:356
	ds_read_b32 v198, v210 offset:616
	ds_read_b32 v199, v210 offset:876
	ds_read_b32 v200, v210 offset:1136
	ds_read_b32 v201, v210 offset:1396
	ds_read_b32 v202, v210 offset:1656
	ds_read_b32 v203, v210 offset:1916
	s_waitcnt lgkmcnt(0)
	v_cvt_pk_bf16_f32 v204, v196, v197
	v_cvt_pk_bf16_f32 v205, v198, v199
	v_cvt_pk_bf16_f32 v206, v200, v201
	v_cvt_pk_bf16_f32 v207, v202, v203
	global_store_dwordx4 v211, v[204:207], s[8:9] nt
	s_add_u32 s8, s8, 0x16000
	s_addc_u32 s9, s9, 0
	s_nop 1
	ds_read_b32 v196, v210 offset:128
	ds_read_b32 v197, v210 offset:388
	ds_read_b32 v198, v210 offset:648
	ds_read_b32 v199, v210 offset:908
	ds_read_b32 v200, v210 offset:1168
	ds_read_b32 v201, v210 offset:1428
	ds_read_b32 v202, v210 offset:1688
	ds_read_b32 v203, v210 offset:1948
	s_waitcnt lgkmcnt(0)
	v_cvt_pk_bf16_f32 v204, v196, v197
	v_cvt_pk_bf16_f32 v205, v198, v199
	v_cvt_pk_bf16_f32 v206, v200, v201
	v_cvt_pk_bf16_f32 v207, v202, v203
	global_store_dwordx4 v211, v[204:207], s[8:9] nt
	s_add_u32 s8, s8, 0x16000
	s_addc_u32 s9, s9, 0
	s_nop 1
	ds_read_b32 v196, v210 offset:160
	ds_read_b32 v197, v210 offset:420
	ds_read_b32 v198, v210 offset:680
	ds_read_b32 v199, v210 offset:940
	ds_read_b32 v200, v210 offset:1200
	ds_read_b32 v201, v210 offset:1460
	ds_read_b32 v202, v210 offset:1720
	ds_read_b32 v203, v210 offset:1980
	s_waitcnt lgkmcnt(0)
	v_cvt_pk_bf16_f32 v204, v196, v197
	v_cvt_pk_bf16_f32 v205, v198, v199
	v_cvt_pk_bf16_f32 v206, v200, v201
	v_cvt_pk_bf16_f32 v207, v202, v203
	global_store_dwordx4 v211, v[204:207], s[8:9] nt
	s_add_u32 s8, s8, 0x16000
	s_addc_u32 s9, s9, 0
	s_nop 1
	ds_read_b32 v196, v210 offset:192
	ds_read_b32 v197, v210 offset:452
	ds_read_b32 v198, v210 offset:712
	ds_read_b32 v199, v210 offset:972
	ds_read_b32 v200, v210 offset:1232
	ds_read_b32 v201, v210 offset:1492
	ds_read_b32 v202, v210 offset:1752
	ds_read_b32 v203, v210 offset:2012
	s_waitcnt lgkmcnt(0)
	v_cvt_pk_bf16_f32 v204, v196, v197
	v_cvt_pk_bf16_f32 v205, v198, v199
	v_cvt_pk_bf16_f32 v206, v200, v201
	v_cvt_pk_bf16_f32 v207, v202, v203
	global_store_dwordx4 v211, v[204:207], s[8:9] nt
	s_add_u32 s8, s8, 0x16000
	s_addc_u32 s9, s9, 0
	s_nop 1
	ds_read_b32 v196, v210 offset:224
	ds_read_b32 v197, v210 offset:484
	ds_read_b32 v198, v210 offset:744
	ds_read_b32 v199, v210 offset:1004
	ds_read_b32 v200, v210 offset:1264
	ds_read_b32 v201, v210 offset:1524
	ds_read_b32 v202, v210 offset:1784
	ds_read_b32 v203, v210 offset:2044
	s_waitcnt lgkmcnt(0)
	v_cvt_pk_bf16_f32 v204, v196, v197
	v_cvt_pk_bf16_f32 v205, v198, v199
	v_cvt_pk_bf16_f32 v206, v200, v201
	v_cvt_pk_bf16_f32 v207, v202, v203
	global_store_dwordx4 v211, v[204:207], s[8:9] nt
	s_nop 1
	s_add_i32 s4, s13, 0x400
	s_waitcnt vmcnt(0)
	ds_write_b32 v209, v68 offset:0
	ds_write_b32 v209, v69 offset:4
	ds_write_b32 v209, v70 offset:8
	ds_write_b32 v209, v71 offset:12
	ds_write_b32 v209, v72 offset:1040
	ds_write_b32 v209, v73 offset:1044
	ds_write_b32 v209, v74 offset:1048
	ds_write_b32 v209, v75 offset:1052
	ds_write_b32 v209, v76 offset:2080
	ds_write_b32 v209, v77 offset:2084
	ds_write_b32 v209, v78 offset:2088
	ds_write_b32 v209, v79 offset:2092
	ds_write_b32 v209, v80 offset:3120
	ds_write_b32 v209, v81 offset:3124
	ds_write_b32 v209, v82 offset:3128
	ds_write_b32 v209, v83 offset:3132
	ds_write_b32 v209, v84 offset:4160
	ds_write_b32 v209, v85 offset:4164
	ds_write_b32 v209, v86 offset:4168
	ds_write_b32 v209, v87 offset:4172
	ds_write_b32 v209, v88 offset:5200
	ds_write_b32 v209, v89 offset:5204
	ds_write_b32 v209, v90 offset:5208
	ds_write_b32 v209, v91 offset:5212
	ds_write_b32 v209, v92 offset:6240
	ds_write_b32 v209, v93 offset:6244
	ds_write_b32 v209, v94 offset:6248
	ds_write_b32 v209, v95 offset:6252
	ds_write_b32 v209, v96 offset:7280
	ds_write_b32 v209, v97 offset:7284
	ds_write_b32 v209, v98 offset:7288
	ds_write_b32 v209, v99 offset:7292
	ds_write_b32 v209, v100 offset:8320
	ds_write_b32 v209, v101 offset:8324
	ds_write_b32 v209, v102 offset:8328
	ds_write_b32 v209, v103 offset:8332
	ds_write_b32 v209, v104 offset:9360
	ds_write_b32 v209, v105 offset:9364
	ds_write_b32 v209, v106 offset:9368
	ds_write_b32 v209, v107 offset:9372
	ds_write_b32 v209, v108 offset:10400
	ds_write_b32 v209, v109 offset:10404
	ds_write_b32 v209, v110 offset:10408
	ds_write_b32 v209, v111 offset:10412
	ds_write_b32 v209, v112 offset:11440
	ds_write_b32 v209, v113 offset:11444
	ds_write_b32 v209, v114 offset:11448
	ds_write_b32 v209, v115 offset:11452
	ds_write_b32 v209, v116 offset:12480
	ds_write_b32 v209, v117 offset:12484
	ds_write_b32 v209, v118 offset:12488
	ds_write_b32 v209, v119 offset:12492
	ds_write_b32 v209, v120 offset:13520
	ds_write_b32 v209, v121 offset:13524
	ds_write_b32 v209, v122 offset:13528
	ds_write_b32 v209, v123 offset:13532
	ds_write_b32 v209, v124 offset:14560
	ds_write_b32 v209, v125 offset:14564
	ds_write_b32 v209, v126 offset:14568
	ds_write_b32 v209, v127 offset:14572
	ds_write_b32 v209, v128 offset:15600
	ds_write_b32 v209, v129 offset:15604
	ds_write_b32 v209, v130 offset:15608
	ds_write_b32 v209, v131 offset:15612
	s_lshr_b32 s5, s4, 5
	s_and_b32 s6, s4, 31
	s_mul_i32 s6, s6, 0xb0000
	s_lshl_b32 s5, s5, 7
	s_add_u32 s8, s2, s6
	s_addc_u32 s9, s3, 0
	s_add_u32 s8, s8, s5
	s_addc_u32 s9, s9, 0
	s_waitcnt lgkmcnt(0)
	ds_read_b32 v196, v210 offset:0
	ds_read_b32 v197, v210 offset:260
	ds_read_b32 v198, v210 offset:520
	ds_read_b32 v199, v210 offset:780
	ds_read_b32 v200, v210 offset:1040
	ds_read_b32 v201, v210 offset:1300
	ds_read_b32 v202, v210 offset:1560
	ds_read_b32 v203, v210 offset:1820
	s_waitcnt lgkmcnt(0)
	v_cvt_pk_bf16_f32 v204, v196, v197
	v_cvt_pk_bf16_f32 v205, v198, v199
	v_cvt_pk_bf16_f32 v206, v200, v201
	v_cvt_pk_bf16_f32 v207, v202, v203
	global_store_dwordx4 v211, v[204:207], s[8:9] nt
	s_add_u32 s8, s8, 0x16000
	s_addc_u32 s9, s9, 0
	s_nop 1
	ds_read_b32 v196, v210 offset:32
	ds_read_b32 v197, v210 offset:292
	ds_read_b32 v198, v210 offset:552
	ds_read_b32 v199, v210 offset:812
	ds_read_b32 v200, v210 offset:1072
	ds_read_b32 v201, v210 offset:1332
	ds_read_b32 v202, v210 offset:1592
	ds_read_b32 v203, v210 offset:1852
	s_waitcnt lgkmcnt(0)
	v_cvt_pk_bf16_f32 v204, v196, v197
	v_cvt_pk_bf16_f32 v205, v198, v199
	v_cvt_pk_bf16_f32 v206, v200, v201
	v_cvt_pk_bf16_f32 v207, v202, v203
	global_store_dwordx4 v211, v[204:207], s[8:9] nt
	s_add_u32 s8, s8, 0x16000
	s_addc_u32 s9, s9, 0
	s_nop 1
	ds_read_b32 v196, v210 offset:64
	ds_read_b32 v197, v210 offset:324
	ds_read_b32 v198, v210 offset:584
	ds_read_b32 v199, v210 offset:844
	ds_read_b32 v200, v210 offset:1104
	ds_read_b32 v201, v210 offset:1364
	ds_read_b32 v202, v210 offset:1624
	ds_read_b32 v203, v210 offset:1884
	s_waitcnt lgkmcnt(0)
	v_cvt_pk_bf16_f32 v204, v196, v197
	v_cvt_pk_bf16_f32 v205, v198, v199
	v_cvt_pk_bf16_f32 v206, v200, v201
	v_cvt_pk_bf16_f32 v207, v202, v203
	global_store_dwordx4 v211, v[204:207], s[8:9] nt
	s_add_u32 s8, s8, 0x16000
	s_addc_u32 s9, s9, 0
	s_nop 1
	ds_read_b32 v196, v210 offset:96
	ds_read_b32 v197, v210 offset:356
	ds_read_b32 v198, v210 offset:616
	ds_read_b32 v199, v210 offset:876
	ds_read_b32 v200, v210 offset:1136
	ds_read_b32 v201, v210 offset:1396
	ds_read_b32 v202, v210 offset:1656
	ds_read_b32 v203, v210 offset:1916
	s_waitcnt lgkmcnt(0)
	v_cvt_pk_bf16_f32 v204, v196, v197
	v_cvt_pk_bf16_f32 v205, v198, v199
	v_cvt_pk_bf16_f32 v206, v200, v201
	v_cvt_pk_bf16_f32 v207, v202, v203
	global_store_dwordx4 v211, v[204:207], s[8:9] nt
	s_add_u32 s8, s8, 0x16000
	s_addc_u32 s9, s9, 0
	s_nop 1
	ds_read_b32 v196, v210 offset:128
	ds_read_b32 v197, v210 offset:388
	ds_read_b32 v198, v210 offset:648
	ds_read_b32 v199, v210 offset:908
	ds_read_b32 v200, v210 offset:1168
	ds_read_b32 v201, v210 offset:1428
	ds_read_b32 v202, v210 offset:1688
	ds_read_b32 v203, v210 offset:1948
	s_waitcnt lgkmcnt(0)
	v_cvt_pk_bf16_f32 v204, v196, v197
	v_cvt_pk_bf16_f32 v205, v198, v199
	v_cvt_pk_bf16_f32 v206, v200, v201
	v_cvt_pk_bf16_f32 v207, v202, v203
	global_store_dwordx4 v211, v[204:207], s[8:9] nt
	s_add_u32 s8, s8, 0x16000
	s_addc_u32 s9, s9, 0
	s_nop 1
	ds_read_b32 v196, v210 offset:160
	ds_read_b32 v197, v210 offset:420
	ds_read_b32 v198, v210 offset:680
	ds_read_b32 v199, v210 offset:940
	ds_read_b32 v200, v210 offset:1200
	ds_read_b32 v201, v210 offset:1460
	ds_read_b32 v202, v210 offset:1720
	ds_read_b32 v203, v210 offset:1980
	s_waitcnt lgkmcnt(0)
	v_cvt_pk_bf16_f32 v204, v196, v197
	v_cvt_pk_bf16_f32 v205, v198, v199
	v_cvt_pk_bf16_f32 v206, v200, v201
	v_cvt_pk_bf16_f32 v207, v202, v203
	global_store_dwordx4 v211, v[204:207], s[8:9] nt
	s_add_u32 s8, s8, 0x16000
	s_addc_u32 s9, s9, 0
	s_nop 1
	ds_read_b32 v196, v210 offset:192
	ds_read_b32 v197, v210 offset:452
	ds_read_b32 v198, v210 offset:712
	ds_read_b32 v199, v210 offset:972
	ds_read_b32 v200, v210 offset:1232
	ds_read_b32 v201, v210 offset:1492
	ds_read_b32 v202, v210 offset:1752
	ds_read_b32 v203, v210 offset:2012
	s_waitcnt lgkmcnt(0)
	v_cvt_pk_bf16_f32 v204, v196, v197
	v_cvt_pk_bf16_f32 v205, v198, v199
	v_cvt_pk_bf16_f32 v206, v200, v201
	v_cvt_pk_bf16_f32 v207, v202, v203
	global_store_dwordx4 v211, v[204:207], s[8:9] nt
	s_add_u32 s8, s8, 0x16000
	s_addc_u32 s9, s9, 0
	s_nop 1
	ds_read_b32 v196, v210 offset:224
	ds_read_b32 v197, v210 offset:484
	ds_read_b32 v198, v210 offset:744
	ds_read_b32 v199, v210 offset:1004
	ds_read_b32 v200, v210 offset:1264
	ds_read_b32 v201, v210 offset:1524
	ds_read_b32 v202, v210 offset:1784
	ds_read_b32 v203, v210 offset:2044
	s_waitcnt lgkmcnt(0)
	v_cvt_pk_bf16_f32 v204, v196, v197
	v_cvt_pk_bf16_f32 v205, v198, v199
	v_cvt_pk_bf16_f32 v206, v200, v201
	v_cvt_pk_bf16_f32 v207, v202, v203
	global_store_dwordx4 v211, v[204:207], s[8:9] nt
	s_nop 1
.Lwd_fin:
	s_waitcnt vmcnt(0) lgkmcnt(0)
